# prologue: adaLN workgroups keep 6 of 10 weight-copy rounds, the other waves take the remaining items
# baseline (speedup 1.0000x reference)
.LBB0_20:
	s_cmpk_eq_i32 s48, 0x800
	s_cbranch_scc0 .Lit_orig
	s_cmp_lt_u32 s2, 0x48
	s_cbranch_scc0 .Lit_other
	s_add_i32 s44, s44, s48
	s_cmpk_lt_i32 s44, 0x3000
	s_cbranch_scc1 .LBB0_21
	s_branch .LBB0_63

.Lit_extra:
	s_cmpk_ge_i32 s85, 0x900
	s_cbranch_scc1 .LBB0_63
	s_mul_i32 s86, s85, 0xe39
	s_lshr_b32 s86, s86, 21
	s_mul_i32 s87, s86, 0x240
	s_sub_i32 s87, s85, s87
	s_add_i32 s86, s86, 6
	s_lshl_b32 s86, s86, 11
	s_add_i32 s44, s86, s87
	s_addk_i32 s85, 0x5c0
	s_branch .LBB0_21
